# v33 + combined attention micro-edits: FoX bias reads hoisted (both half-trips), NSA window ballot pair removed, post-swap self-max pairs removed
# speedup vs baseline: 1.0011x; 1.0011x over previous
.LBB0_787:
	ds_read_b128 v[236:239], v196
	ds_read_b128 v[240:243], v196 offset:32
	ds_read_b128 v[244:247], v196 offset:64
	v_add_u32_e32 v180, s10, v229
	ds_read_b64_tr_b16 v[176:177], v180 offset:24576
	ds_read_b64_tr_b16 v[178:179], v180 offset:25088
	v_add_f32_e32 v80, v64, v65
	v_add_f32_e32 v80, v66, v80
	v_add_f32_e32 v80, v67, v80
	v_add_f32_e32 v80, v68, v80
	v_add_f32_e32 v96, v69, v80
	v_mfma_f32_32x32x16_bf16 v[80:95], v[172:175], v[128:131], v[32:47]
	v_cvt_pk_bf16_f32 v140, v64, v65
	v_cvt_pk_bf16_f32 v141, v66, v67
	ds_read_b64_tr_b16 v[172:173], v180 offset:28672
	ds_read_b64_tr_b16 v[174:175], v180 offset:29184
	v_add_f32_e32 v64, v70, v96
	v_add_f32_e32 v64, v71, v64
	v_add_f32_e32 v64, v72, v64
	v_add_f32_e32 v64, v73, v64
	v_cvt_pk_bf16_f32 v142, v68, v69
	v_cvt_pk_bf16_f32 v143, v70, v71
	v_mfma_f32_32x32x16_bf16 v[96:111], v[168:171], v[128:131], v[32:47]
	ds_read_b64_tr_b16 v[168:169], v180 offset:25600
	ds_read_b64_tr_b16 v[170:171], v180 offset:26112
	v_mfma_f32_32x32x16_bf16 v[80:95], v[164:167], v[120:123], v[80:95]
	v_add_f32_e32 v64, v74, v64
	v_add_f32_e32 v64, v75, v64
	v_add_f32_e32 v64, v76, v64
	v_add_f32_e32 v64, v77, v64
	v_cvt_pk_bf16_f32 v136, v72, v73
	v_cvt_pk_bf16_f32 v137, v74, v75
	ds_read_b64_tr_b16 v[164:165], v180 offset:29696
	ds_read_b64_tr_b16 v[166:167], v180 offset:30208
	v_add_f32_e32 v64, v78, v64
	v_add_f32_e32 v64, v79, v64
	v_add_f32_e32 v64, v48, v64
	v_add_f32_e32 v64, v49, v64
	v_cvt_pk_bf16_f32 v138, v76, v77
	v_cvt_pk_bf16_f32 v139, v78, v79
	v_mfma_f32_32x32x16_bf16 v[96:111], v[160:163], v[120:123], v[96:111]
	ds_read_b64_tr_b16 v[160:161], v180 offset:26624
	ds_read_b64_tr_b16 v[162:163], v180 offset:27136
	v_mfma_f32_32x32x16_bf16 v[80:95], v[156:159], v[116:119], v[80:95]
	v_add_f32_e32 v64, v50, v64
	v_add_f32_e32 v64, v51, v64
	v_add_f32_e32 v64, v52, v64
	v_add_f32_e32 v64, v53, v64
	v_cvt_pk_bf16_f32 v132, v48, v49
	v_cvt_pk_bf16_f32 v133, v50, v51
	ds_read_b64_tr_b16 v[156:157], v180 offset:30720
	ds_read_b64_tr_b16 v[158:159], v180 offset:31232
	v_add_f32_e32 v48, v54, v64
	v_add_f32_e32 v48, v55, v48
	v_add_f32_e32 v48, v56, v48
	v_add_f32_e32 v48, v57, v48
	v_cvt_pk_bf16_f32 v134, v52, v53
	v_cvt_pk_bf16_f32 v135, v54, v55
	v_mfma_f32_32x32x16_bf16 v[96:111], v[152:155], v[116:119], v[96:111]
	ds_read_b64_tr_b16 v[152:153], v180 offset:27648
	ds_read_b64_tr_b16 v[154:155], v180 offset:28160
	v_mfma_f32_32x32x16_bf16 v[80:95], v[148:151], v[112:115], v[80:95]
	v_add_f32_e32 v48, v58, v48
	v_add_f32_e32 v48, v59, v48
	v_add_f32_e32 v48, v60, v48
	v_add_f32_e32 v48, v61, v48
	v_cvt_pk_bf16_f32 v124, v56, v57
	v_cvt_pk_bf16_f32 v125, v58, v59
	ds_read_b64_tr_b16 v[148:149], v180 offset:31744
	ds_read_b64_tr_b16 v[150:151], v180 offset:32256
	v_add_f32_e32 v48, v62, v48
	v_add_f32_e32 v48, v63, v48
	v_add_f32_e32 v180, 0, v48
	v_cvt_pk_bf16_f32 v126, v60, v61
	v_cvt_pk_bf16_f32 v127, v62, v63
	v_mfma_f32_32x32x16_bf16 v[96:111], v[144:147], v[112:115], v[96:111]
	s_waitcnt lgkmcnt(8)
	ds_read_b128 v[76:79], v196 offset:96
	ds_read_b128 v[52:55], v196 offset:160
	ds_read_b128 v[56:59], v196 offset:192
	ds_read_b128 v[60:63], v196 offset:224
	v_lshl_add_u64 v[48:49], v[194:195], 0, s[24:25]
	s_add_i32 s0, s36, s65
	s_mov_b32 m0, s0
	s_nop 0
	global_load_lds_dwordx4 v[48:49], off
	v_lshl_add_u64 v[48:49], v[192:193], 0, s[24:25]
	s_add_i32 s0, s1, s68
	s_mov_b32 m0, s0
	s_nop 0
	global_load_lds_dwordx4 v[48:49], off
	ds_read_b128 v[48:51], v196 offset:128
	s_waitcnt lgkmcnt(4)
	v_add_f32_e32 v64, v80, v236
	v_add_f32_e32 v65, v81, v237
	v_add_f32_e32 v66, v82, v238
	v_add_f32_e32 v67, v83, v239
	v_add_f32_e32 v68, v84, v240
	v_add_f32_e32 v69, v85, v241
	v_add_f32_e32 v70, v86, v242
	v_add_f32_e32 v71, v87, v243
	v_add_f32_e32 v72, v88, v244
	v_add_f32_e32 v73, v89, v245
	v_add_f32_e32 v74, v90, v246
	v_add_f32_e32 v75, v91, v247
	v_add_f32_e32 v76, v92, v76
	v_add_f32_e32 v77, v93, v77
	v_add_f32_e32 v78, v94, v78
	v_add_f32_e32 v79, v95, v79
	s_waitcnt lgkmcnt(1)
	v_add_f32_e32 v52, v100, v52
	v_add_f32_e32 v53, v101, v53
	v_add_f32_e32 v54, v102, v54
	v_add_f32_e32 v55, v103, v55
	v_add_f32_e32 v56, v104, v56
	v_add_f32_e32 v57, v105, v57
	v_add_f32_e32 v58, v106, v58
	v_add_f32_e32 v59, v107, v59
	v_add_f32_e32 v60, v108, v60
	v_add_f32_e32 v61, v109, v61
	v_add_f32_e32 v62, v110, v62
	v_add_f32_e32 v63, v111, v63
	s_waitcnt lgkmcnt(0)
	v_add_f32_e32 v48, v96, v48
	v_add_f32_e32 v49, v97, v49
	v_add_f32_e32 v50, v98, v50
	v_add_f32_e32 v51, v99, v51
	v_max_f32_e32 v80, v64, v65
	v_max3_f32 v81, v66, v67, v49
	v_max3_f32 v80, v80, v48, v50
	v_max3_f32 v80, v80, v51, v68
	v_max3_f32 v81, v81, v70, v71
	v_max3_f32 v80, v80, v69, v52
	v_max3_f32 v81, v81, v54, v55
	v_max3_f32 v80, v80, v53, v72
	v_max3_f32 v81, v81, v74, v75
	v_max3_f32 v80, v80, v73, v56
	v_max3_f32 v81, v81, v58, v59
	v_max3_f32 v80, v80, v57, v76
	v_max3_f32 v81, v81, v78, v79
	v_max3_f32 v80, v80, v77, v60
	v_max3_f32 v81, v81, v62, v63
	v_max3_f32 v80, v80, v61, v81
	v_mov_b32_e32 v81, v80
	s_nop 1
	v_permlane32_swap_b32_e32 v80, v81
	v_max_f32_e32 v80, v80, v81
	v_cmp_lt_f32_e32 vcc, s61, v80
	s_cmp_lg_u64 vcc, 0
	v_add_f32_e32 v197, v231, v180
	s_cselect_b64 s[10:11], -1, 0
	s_cbranch_vccnz .LBB0_795

.LBB0_790:
	ds_read_b128 v[236:239], v196 offset:256
	ds_read_b128 v[240:243], v196 offset:288
	ds_read_b128 v[244:247], v196 offset:320
	s_add_i32 s0, s1, 0x2000
	s_cmpk_lg_i32 s1, 0x4000
	s_cselect_b32 s71, s0, 0
	v_add_u32_e32 v198, s36, v229
	ds_read_b64_tr_b16 v[160:161], v198 offset:24576
	ds_read_b64_tr_b16 v[162:163], v198 offset:25088
	v_add_f32_e32 v80, v64, v65
	v_add_f32_e32 v80, v66, v80
	v_add_f32_e32 v80, v67, v80
	v_add_f32_e32 v80, v68, v80
	v_add_f32_e32 v100, v69, v80
	v_mfma_f32_32x32x16_bf16 v[80:95], v[96:99], v[128:131], v[32:47]
	v_cvt_pk_bf16_f32 v140, v64, v65
	v_cvt_pk_bf16_f32 v141, v66, v67
	ds_read_b64_tr_b16 v[156:157], v198 offset:28672
	ds_read_b64_tr_b16 v[158:159], v198 offset:29184
	v_add_f32_e32 v64, v70, v100
	v_add_f32_e32 v64, v71, v64
	v_add_f32_e32 v64, v72, v64
	v_add_f32_e32 v64, v73, v64
	v_cvt_pk_bf16_f32 v142, v68, v69
	v_cvt_pk_bf16_f32 v143, v70, v71
	v_mfma_f32_32x32x16_bf16 v[96:111], v[180:183], v[128:131], v[32:47]
	ds_read_b64_tr_b16 v[152:153], v198 offset:25600
	ds_read_b64_tr_b16 v[154:155], v198 offset:26112
	v_mfma_f32_32x32x16_bf16 v[80:95], v[184:187], v[120:123], v[80:95]
	v_add_f32_e32 v64, v74, v64
	v_add_f32_e32 v64, v75, v64
	v_add_f32_e32 v64, v76, v64
	v_add_f32_e32 v64, v77, v64
	v_cvt_pk_bf16_f32 v136, v72, v73
	v_cvt_pk_bf16_f32 v137, v74, v75
	ds_read_b64_tr_b16 v[148:149], v198 offset:29696
	ds_read_b64_tr_b16 v[150:151], v198 offset:30208
	v_add_f32_e32 v64, v78, v64
	v_add_f32_e32 v64, v79, v64
	v_add_f32_e32 v64, v48, v64
	v_add_f32_e32 v64, v49, v64
	v_cvt_pk_bf16_f32 v138, v76, v77
	v_cvt_pk_bf16_f32 v139, v78, v79
	v_mfma_f32_32x32x16_bf16 v[96:111], v[144:147], v[120:123], v[96:111]
	ds_read_b64_tr_b16 v[144:145], v198 offset:26624
	ds_read_b64_tr_b16 v[146:147], v198 offset:27136
	v_mfma_f32_32x32x16_bf16 v[80:95], v[176:179], v[116:119], v[80:95]
	v_add_f32_e32 v64, v50, v64
	v_add_f32_e32 v64, v51, v64
	v_add_f32_e32 v64, v52, v64
	v_add_f32_e32 v64, v53, v64
	v_cvt_pk_bf16_f32 v132, v48, v49
	v_cvt_pk_bf16_f32 v133, v50, v51
	ds_read_b64_tr_b16 v[184:185], v198 offset:30720
	ds_read_b64_tr_b16 v[186:187], v198 offset:31232
	v_add_f32_e32 v48, v54, v64
	v_add_f32_e32 v48, v55, v48
	v_add_f32_e32 v48, v56, v48
	v_add_f32_e32 v48, v57, v48
	v_cvt_pk_bf16_f32 v134, v52, v53
	v_cvt_pk_bf16_f32 v135, v54, v55
	v_mfma_f32_32x32x16_bf16 v[96:111], v[168:171], v[116:119], v[96:111]
	ds_read_b64_tr_b16 v[180:181], v198 offset:27648
	ds_read_b64_tr_b16 v[182:183], v198 offset:28160
	v_mfma_f32_32x32x16_bf16 v[80:95], v[172:175], v[112:115], v[80:95]
	v_add_f32_e32 v48, v58, v48
	v_add_f32_e32 v48, v59, v48
	v_add_f32_e32 v48, v60, v48
	v_add_f32_e32 v48, v61, v48
	v_cvt_pk_bf16_f32 v124, v56, v57
	v_cvt_pk_bf16_f32 v125, v58, v59
	ds_read_b64_tr_b16 v[176:177], v198 offset:31744
	ds_read_b64_tr_b16 v[178:179], v198 offset:32256
	v_add_f32_e32 v48, v62, v48
	v_add_f32_e32 v48, v63, v48
	v_add_f32_e32 v168, 0, v48
	v_cvt_pk_bf16_f32 v126, v60, v61
	v_cvt_pk_bf16_f32 v127, v62, v63
	v_mfma_f32_32x32x16_bf16 v[96:111], v[164:167], v[112:115], v[96:111]
	s_waitcnt lgkmcnt(8)
	ds_read_b128 v[76:79], v196 offset:352
	ds_read_b128 v[48:51], v196 offset:384
	ds_read_b128 v[52:55], v196 offset:416
	ds_read_b128 v[56:59], v196 offset:448
	ds_read_b128 v[60:63], v196 offset:480
	s_add_i32 s0, s1, s65
	s_mov_b32 m0, s0
	s_nop 0
	global_load_lds_dwordx4 v[194:195], off
	s_add_i32 s0, s71, s68
	s_mov_b32 m0, s0
	s_nop 0
	global_load_lds_dwordx4 v[192:193], off
	s_waitcnt lgkmcnt(4)
	v_add_f32_e32 v64, v80, v236
	v_add_f32_e32 v65, v81, v237
	v_add_f32_e32 v66, v82, v238
	v_add_f32_e32 v67, v83, v239
	v_add_f32_e32 v68, v84, v240
	v_add_f32_e32 v69, v85, v241
	v_add_f32_e32 v70, v86, v242
	v_add_f32_e32 v71, v87, v243
	v_add_f32_e32 v72, v88, v244
	v_add_f32_e32 v73, v89, v245
	v_add_f32_e32 v74, v90, v246
	v_add_f32_e32 v75, v91, v247
	v_add_f32_e32 v76, v92, v76
	v_add_f32_e32 v77, v93, v77
	v_add_f32_e32 v78, v94, v78
	v_add_f32_e32 v79, v95, v79
	s_waitcnt lgkmcnt(1)
	v_add_f32_e32 v48, v96, v48
	v_add_f32_e32 v49, v97, v49
	v_add_f32_e32 v50, v98, v50
	v_add_f32_e32 v51, v99, v51
	v_add_f32_e32 v52, v100, v52
	v_add_f32_e32 v53, v101, v53
	v_add_f32_e32 v54, v102, v54
	v_add_f32_e32 v55, v103, v55
	v_add_f32_e32 v56, v104, v56
	v_add_f32_e32 v57, v105, v57
	v_add_f32_e32 v58, v106, v58
	v_add_f32_e32 v59, v107, v59
	s_waitcnt lgkmcnt(0)
	v_add_f32_e32 v60, v108, v60
	v_add_f32_e32 v61, v109, v61
	v_add_f32_e32 v62, v110, v62
	v_add_f32_e32 v63, v111, v63
	v_max_f32_e32 v80, v64, v65
	v_max3_f32 v81, v66, v67, v49
	v_max3_f32 v80, v80, v48, v50
	v_max3_f32 v80, v80, v51, v68
	v_max3_f32 v81, v81, v70, v71
	v_max3_f32 v80, v80, v69, v52
	v_max3_f32 v81, v81, v54, v55
	v_max3_f32 v80, v80, v53, v72
	v_max3_f32 v81, v81, v74, v75
	v_max3_f32 v80, v80, v73, v56
	v_max3_f32 v81, v81, v58, v59
	v_max3_f32 v80, v80, v57, v76
	v_max3_f32 v81, v81, v78, v79
	v_max3_f32 v80, v80, v77, v60
	v_max3_f32 v81, v81, v62, v63
	v_max3_f32 v80, v80, v61, v81
	v_mov_b32_e32 v81, v80
	s_nop 1
	v_permlane32_swap_b32_e32 v80, v81
	v_max_f32_e32 v80, v80, v81
	v_cmp_lt_f32_e32 vcc, s61, v80
	s_cmp_lg_u64 vcc, 0
	v_add_f32_e32 v231, v197, v168
	s_cselect_b64 s[10:11], -1, 0
	s_cbranch_vccnz .LBB0_798

.LBB0_965:
	v_add_u32_e32 v10, s50, v188
	v_add3_u32 v114, v10, v181, v180
	v_add_u32_e32 v115, v10, v182
	ds_read_b64_tr_b16 v[6:7], v114 offset:8192
	ds_read_b64_tr_b16 v[8:9], v114 offset:9216
	ds_read_b64_tr_b16 v[10:11], v115 offset:8192
	ds_read_b64_tr_b16 v[12:13], v115 offset:9216
	s_nop 2
	v_max_f32_e32 v2, v97, v97
	v_max_f32_e32 v3, v96, v96
	v_max_f32_e32 v2, v3, v2
	v_max3_f32 v3, v98, v99, v81
	v_max3_f32 v2, v2, v80, v82
	v_max3_f32 v2, v2, v83, v100
	v_max3_f32 v3, v3, v102, v103
	v_max3_f32 v2, v2, v101, v84
	v_max3_f32 v3, v3, v86, v87
	v_max3_f32 v2, v2, v85, v104
	v_max3_f32 v3, v3, v106, v107
	v_max3_f32 v2, v2, v105, v88
	v_max3_f32 v3, v3, v90, v91
	v_max3_f32 v2, v2, v89, v108
	v_max3_f32 v3, v3, v110, v111
	v_max3_f32 v2, v2, v109, v92
	v_max3_f32 v3, v3, v94, v95
	v_max3_f32 v2, v2, v93, v3
	v_mov_b32_e32 v3, v2
	s_nop 1
	v_permlane32_swap_b32_e32 v2, v3
	s_xor_b64 s[6:7], s[62:63], -1
	v_max_f32_e32 v2, v2, v3
	s_and_b64 s[4:5], s[62:63], exec
	s_andn2_b64 vcc, exec, s[6:7]
	s_mov_b64 s[6:7], -1
	s_cbranch_vccnz .LBB0_968
	v_cmp_lt_f32_e32 vcc, s91, v2
	s_cbranch_vccz .LBB0_974
	s_nop 0
	v_cndmask_b32_e32 v2, 0, v2, vcc
